# LayerNorm phases: wave-wide sums via DPP row ops + readlane instead of six ds_bpermute round trips each
# speedup vs baseline: 1.0091x; 1.0051x over previous
.LBB0_163:
	s_add_i32 s0, s46, 0xffff8000
	s_cmpk_gt_i32 s46, 0x7fff
	s_cselect_b32 s0, s0, s46
	s_cselect_b32 s1, s56, s52
	s_cselect_b32 s10, s57, s53
	s_cselect_b32 s11, s33, s78
	s_cselect_b32 s16, s73, s79
	s_and_b64 s[8:9], s[6:7], exec
	s_cselect_b32 s8, s10, s16
	s_cselect_b32 s9, s1, s11
	s_ashr_i32 s1, s0, 31
	s_lshl_b64 s[0:1], s[0:1], 12
	s_add_u32 s0, s9, s0
	s_addc_u32 s1, s8, s1
	s_add_i32 s49, s12, s46
	s_cmp_lt_i32 s49, s13
	v_lshlrev_b32_e32 v0, 4, v66
	s_cselect_b64 s[10:11], -1, 0
	global_load_dwordx4 v[62:65], v0, s[0:1]
	global_load_dwordx4 v[58:61], v0, s[0:1] offset:1024
	global_load_dwordx4 v[54:57], v0, s[0:1] offset:2048
	global_load_dwordx4 v[50:53], v0, s[0:1] offset:3072
	s_and_b64 s[0:1], s[10:11], exec
	s_cselect_b32 s8, s49, s46
	s_cmpk_gt_i32 s8, 0x7fff
	s_cselect_b64 s[0:1], -1, 0
	s_add_i32 s9, s8, 0xffff8000
	s_and_b64 s[0:1], s[0:1], exec
	s_cselect_b32 s0, s9, s8
	s_cselect_b32 s1, s56, s52
	s_cselect_b32 s16, s57, s53
	s_cselect_b32 s17, s33, s78
	s_cselect_b32 s20, s73, s79
	s_and_b64 s[8:9], s[6:7], exec
	s_cselect_b32 s8, s16, s20
	s_cselect_b32 s9, s1, s17
	s_ashr_i32 s1, s0, 31
	s_lshl_b64 s[0:1], s[0:1], 12
	s_add_u32 s0, s9, s0
	s_addc_u32 s1, s8, s1
	s_add_i32 s16, s12, s49
	s_cmp_lt_i32 s16, s13
	s_cselect_b64 s[50:51], -1, 0
	global_load_dwordx4 v[46:49], v0, s[0:1]
	global_load_dwordx4 v[42:45], v0, s[0:1] offset:1024
	global_load_dwordx4 v[38:41], v0, s[0:1] offset:2048
	global_load_dwordx4 v[34:37], v0, s[0:1] offset:3072
	s_and_b64 s[0:1], s[50:51], exec
	s_cselect_b32 s8, s16, s46
	s_cmpk_gt_i32 s8, 0x7fff
	s_cselect_b64 s[0:1], -1, 0
	s_add_i32 s9, s8, 0xffff8000
	s_and_b64 s[0:1], s[0:1], exec
	s_cselect_b32 s0, s9, s8
	s_cselect_b32 s1, s56, s52
	s_cselect_b32 s17, s57, s53
	s_cselect_b32 s20, s33, s78
	s_cselect_b32 s22, s73, s79
	s_and_b64 s[8:9], s[6:7], exec
	s_cselect_b32 s8, s17, s22
	s_cselect_b32 s9, s1, s20
	s_ashr_i32 s1, s0, 31
	s_lshl_b64 s[0:1], s[0:1], 12
	s_add_u32 s0, s9, s0
	s_addc_u32 s1, s8, s1
	s_add_i32 s47, s12, s16
	s_cmp_lt_i32 s47, s13
	s_cselect_b64 s[8:9], -1, 0
	global_load_dwordx4 v[30:33], v0, s[0:1]
	global_load_dwordx4 v[26:29], v0, s[0:1] offset:1024
	global_load_dwordx4 v[18:21], v0, s[0:1] offset:2048
	global_load_dwordx4 v[22:25], v0, s[0:1] offset:3072
	s_and_b64 s[0:1], s[8:9], exec
	s_cselect_b32 s16, s47, s46
	s_cmpk_gt_i32 s16, 0x7fff
	s_cselect_b64 s[0:1], -1, 0
	s_add_i32 s17, s16, 0xffff8000
	s_and_b64 s[0:1], s[0:1], exec
	s_cselect_b32 s0, s17, s16
	s_cselect_b32 s1, s56, s52
	s_cselect_b32 s16, s57, s53
	s_cselect_b32 s17, s33, s78
	s_cselect_b32 s20, s73, s79
	s_and_b64 s[38:39], s[6:7], exec
	s_cselect_b32 s16, s16, s20
	s_cselect_b32 s17, s1, s17
	s_ashr_i32 s1, s0, 31
	s_lshl_b64 s[0:1], s[0:1], 12
	s_add_u32 s0, s17, s0
	s_addc_u32 s1, s16, s1
	global_load_dwordx4 v[14:17], v0, s[0:1]
	global_load_dwordx4 v[10:13], v0, s[0:1] offset:1024
	global_load_dwordx4 v[2:5], v0, s[0:1] offset:2048
	global_load_dwordx4 v[6:9], v0, s[0:1] offset:3072
	v_cndmask_b32_e64 v67, 0, 1, s[40:41]
	v_cmp_ne_u32_e64 s[38:39], 1, v67
	s_andn2_b64 vcc, exec, s[40:41]
	s_cbranch_vccnz .LBB0_167
	s_waitcnt vmcnt(0)
	v_mov_b32_e32 v78, v63
	v_mov_b32_e32 v79, v64
	v_mov_b32_e32 v80, v62
	v_mov_b32_e32 v81, v65
	v_pk_add_f32 v[78:79], v[78:79], v[80:81]
	s_waitcnt vmcnt(14)
	v_mov_b32_e32 v80, v59
	v_mov_b32_e32 v81, v60
	v_mov_b32_e32 v82, v58
	v_mov_b32_e32 v83, v61
	v_pk_add_f32 v[80:81], v[80:81], v[82:83]
	v_add_f32_e32 v67, v78, v79
	v_pk_add_f32 v[80:81], v[80:81], v[80:81] op_sel:[0,1] op_sel_hi:[1,0]
	v_add_f32_e32 v78, 0, v67
	s_waitcnt vmcnt(13)
	v_add_f32_e32 v82, v54, v55
	v_add_f32_e32 v84, v56, v57
	s_waitcnt vmcnt(12)
	v_mov_b32_e32 v79, v50
	v_mov_b32_e32 v81, v51
	v_mov_b32_e32 v83, v52
	v_mov_b32_e32 v85, v53
	v_pk_add_f32 v[78:79], v[78:79], v[80:81]
	v_pk_add_f32 v[80:81], v[82:83], v[84:85]
	s_nop 0
	v_pk_add_f32 v[78:79], v[78:79], v[80:81]
	s_nop 0
	v_add_f32_e32 v67, v78, v79
	s_nop 1
	v_add_f32_dpp v67, v67, v67 quad_perm:[1,0,3,2] row_mask:0xf bank_mask:0xf
	s_nop 1
	v_add_f32_dpp v67, v67, v67 quad_perm:[2,3,0,1] row_mask:0xf bank_mask:0xf
	s_nop 1
	v_add_f32_dpp v67, v67, v67 row_half_mirror row_mask:0xf bank_mask:0xf
	s_nop 1
	v_add_f32_dpp v67, v67, v67 row_mirror row_mask:0xf bank_mask:0xf
	s_nop 1
	v_add_f32_dpp v67, v67, v67 row_bcast:15 row_mask:0xa bank_mask:0xf
	s_nop 1
	v_add_f32_dpp v67, v67, v67 row_bcast:31 row_mask:0xc bank_mask:0xf
	s_nop 1
	v_readlane_b32 vcc_lo, v67, 63
	s_nop 1
	v_mov_b32_e32 v67, vcc_lo
	v_fmamk_f32 v65, v67, 0xba800000, v65
	v_fmamk_f32 v63, v67, 0xba800000, v63
	v_fmamk_f32 v64, v67, 0xba800000, v64
	v_fmac_f32_e32 v62, 0xba800000, v67
	v_mul_f32_e32 v84, v63, v63
	v_mul_f32_e32 v85, v65, v65
	v_fmac_f32_e32 v84, v62, v62
	v_fmac_f32_e32 v85, v64, v64
	v_fmamk_f32 v61, v67, 0xba800000, v61
	v_fmamk_f32 v59, v67, 0xba800000, v59
	v_add_f32_e32 v84, v84, v85
	v_fmamk_f32 v60, v67, 0xba800000, v60
	v_fmac_f32_e32 v58, 0xba800000, v67
	v_mul_f32_e32 v85, v59, v59
	v_mul_f32_e32 v86, v61, v61
	v_fmac_f32_e32 v85, v58, v58
	v_fmac_f32_e32 v86, v60, v60
	v_add_f32_e32 v85, v85, v86
	v_fmamk_f32 v57, v67, 0xba800000, v57
	v_fmamk_f32 v55, v67, 0xba800000, v55
	v_add_f32_e32 v84, v84, v85
	v_fmamk_f32 v56, v67, 0xba800000, v56
	v_fmac_f32_e32 v54, 0xba800000, v67
	v_mul_f32_e32 v85, v55, v55
	v_mul_f32_e32 v86, v57, v57
	v_fmac_f32_e32 v85, v54, v54
	v_fmac_f32_e32 v86, v56, v56
	v_add_f32_e32 v85, v85, v86
	v_fmamk_f32 v53, v67, 0xba800000, v53
	v_fmamk_f32 v51, v67, 0xba800000, v51
	v_add_f32_e32 v84, v84, v85
	v_fmamk_f32 v52, v67, 0xba800000, v52
	v_fmac_f32_e32 v50, 0xba800000, v67
	v_mul_f32_e32 v85, v51, v51
	v_mul_f32_e32 v86, v53, v53
	v_fmac_f32_e32 v85, v50, v50
	v_fmac_f32_e32 v86, v52, v52
	v_add_f32_e32 v85, v85, v86
	v_add_f32_e32 v84, v84, v85
	v_mov_b32_e32 v78, v84
	s_nop 1
	v_add_f32_dpp v78, v78, v78 quad_perm:[1,0,3,2] row_mask:0xf bank_mask:0xf
	s_nop 1
	v_add_f32_dpp v78, v78, v78 quad_perm:[2,3,0,1] row_mask:0xf bank_mask:0xf
	s_nop 1
	v_add_f32_dpp v78, v78, v78 row_half_mirror row_mask:0xf bank_mask:0xf
	s_nop 1
	v_add_f32_dpp v78, v78, v78 row_mirror row_mask:0xf bank_mask:0xf
	s_nop 1
	v_add_f32_dpp v78, v78, v78 row_bcast:15 row_mask:0xa bank_mask:0xf
	s_nop 1
	v_add_f32_dpp v78, v78, v78 row_bcast:31 row_mask:0xc bank_mask:0xf
	s_nop 1
	v_readlane_b32 vcc_lo, v78, 63
	s_nop 1
	v_mov_b32_e32 v78, vcc_lo
	v_fmamk_f32 v78, v78, 0x3a800000, v213
	v_mul_f32_e32 v79, 0x4f800000, v78
	v_cmp_gt_f32_e32 vcc, s61, v78
	s_nop 1
	v_cndmask_b32_e32 v78, v78, v79, vcc
	v_sqrt_f32_e32 v79, v78
	s_nop 0
	v_add_u32_e32 v80, -1, v79
	v_fma_f32 v81, -v80, v79, v78
	v_cmp_ge_f32_e64 s[0:1], 0, v81
	v_add_u32_e32 v81, 1, v79
	s_nop 0
	v_cndmask_b32_e64 v80, v79, v80, s[0:1]
	v_fma_f32 v79, -v81, v79, v78
	v_cmp_lt_f32_e64 s[0:1], 0, v79
	s_nop 1
	v_cndmask_b32_e64 v79, v80, v81, s[0:1]
	v_mul_f32_e32 v80, 0x37800000, v79
	v_cndmask_b32_e32 v79, v79, v80, vcc
	v_cmp_class_f32_e32 vcc, v78, v214
	s_nop 1
	v_cndmask_b32_e32 v78, v79, v78, vcc
	v_div_scale_f32 v79, s[0:1], v78, v78, 1.0
	v_rcp_f32_e32 v80, v79
	s_nop 0
	v_fma_f32 v81, -v79, v80, 1.0
	v_fmac_f32_e32 v80, v81, v80
	v_div_scale_f32 v81, vcc, 1.0, v78, 1.0
	v_mul_f32_e32 v82, v81, v80
	v_fma_f32 v83, -v79, v82, v81
	v_fmac_f32_e32 v82, v83, v80
	v_fma_f32 v79, -v79, v82, v81
	v_div_fmas_f32 v79, v79, v80, v82
	v_div_fixup_f32 v78, v79, v78, 1.0
	s_and_saveexec_b64 s[0:1], s[36:37]
	s_cbranch_execz .LBB0_166
	s_add_u32 s62, s90, s29
	v_mul_f32_e32 v80, 0x3a800000, v67
	s_addc_u32 s63, s91, s30
	v_mov_b32_e32 v81, v78
	global_store_dwordx2 v1, v[80:81], s[62:63]

.LBB0_167:
	s_min_i32 s0, s46, 0x8000
	s_ashr_i32 s0, s0, 12
	s_mulk_i32 s0, 0xc00
	s_ashr_i32 s1, s0, 31
	s_lshl_b64 s[0:1], s[0:1], 2
	s_add_u32 s0, s19, s0
	s_addc_u32 s1, s28, s1
	s_add_u32 s16, s0, 0x1000
	s_addc_u32 s17, s1, 0
	global_load_dwordx4 v[120:123], v0, s[0:1]
	global_load_dwordx4 v[124:127], v0, s[0:1] offset:1024
	global_load_dwordx4 v[128:131], v0, s[0:1] offset:2048
	global_load_dwordx4 v[132:135], v0, s[0:1] offset:3072
	global_load_dwordx4 v[136:139], v0, s[16:17]
	global_load_dwordx4 v[140:143], v0, s[16:17] offset:1024
	global_load_dwordx4 v[144:147], v0, s[16:17] offset:2048
	global_load_dwordx4 v[148:151], v0, s[16:17] offset:3072
	v_lshl_add_u64 v[88:89], s[90:91], 0, v[74:75]
	v_add_co_u32_e32 v88, vcc, s70, v88
	v_addc_co_u32_e32 v89, vcc, 0, v89, vcc
	s_waitcnt vmcnt(0)
	v_pk_add_f32 v[138:139], v[138:139], 1.0 op_sel_hi:[1,0]
	v_pk_add_f32 v[136:137], v[136:137], 1.0 op_sel_hi:[1,0]
	v_pk_fma_f32 v[64:65], v[64:65], v[138:139], v[122:123]
	v_pk_fma_f32 v[62:63], v[62:63], v[136:137], v[120:121]
	s_nop 0
	v_cvt_pk_bf16_f32 v62, v62, v63
	v_cvt_pk_bf16_f32 v63, v64, v65
	global_store_dwordx2 v[88:89], v[62:63], off
	v_pk_add_f32 v[142:143], v[142:143], 1.0 op_sel_hi:[1,0]
	v_pk_add_f32 v[140:141], v[140:141], 1.0 op_sel_hi:[1,0]
	v_pk_fma_f32 v[60:61], v[60:61], v[142:143], v[126:127]
	v_pk_fma_f32 v[58:59], v[58:59], v[140:141], v[124:125]
	s_nop 0
	v_cvt_pk_bf16_f32 v58, v58, v59
	v_cvt_pk_bf16_f32 v59, v60, v61
	global_store_dwordx2 v[88:89], v[58:59], off offset:512
	v_pk_add_f32 v[146:147], v[146:147], 1.0 op_sel_hi:[1,0]
	v_pk_add_f32 v[144:145], v[144:145], 1.0 op_sel_hi:[1,0]
	v_pk_fma_f32 v[56:57], v[56:57], v[146:147], v[130:131]
	v_pk_fma_f32 v[54:55], v[54:55], v[144:145], v[128:129]
	s_nop 0
	v_cvt_pk_bf16_f32 v54, v54, v55
	v_cvt_pk_bf16_f32 v55, v56, v57
	global_store_dwordx2 v[88:89], v[54:55], off offset:1024
	v_pk_add_f32 v[150:151], v[150:151], 1.0 op_sel_hi:[1,0]
	v_pk_add_f32 v[148:149], v[148:149], 1.0 op_sel_hi:[1,0]
	v_pk_fma_f32 v[52:53], v[52:53], v[150:151], v[134:135]
	v_pk_fma_f32 v[50:51], v[50:51], v[148:149], v[132:133]
	s_nop 0
	v_cvt_pk_bf16_f32 v50, v50, v51
	v_cvt_pk_bf16_f32 v51, v52, v53
	global_store_dwordx2 v[88:89], v[50:51], off offset:1536
	s_andn2_b64 vcc, exec, s[10:11]
	s_cbranch_vccnz .LBB0_162
	s_and_b64 vcc, exec, s[38:39]
	s_cbranch_vccnz .LBB0_172
	v_mov_b32_e32 v50, v47
	v_mov_b32_e32 v51, v48
	v_mov_b32_e32 v52, v46
	v_mov_b32_e32 v53, v49
	v_pk_add_f32 v[50:51], v[50:51], v[52:53]
	v_mov_b32_e32 v52, v43
	v_mov_b32_e32 v53, v44
	v_mov_b32_e32 v54, v42
	v_mov_b32_e32 v55, v45
	v_pk_add_f32 v[52:53], v[52:53], v[54:55]
	v_add_f32_e32 v50, v50, v51
	v_pk_add_f32 v[52:53], v[52:53], v[52:53] op_sel:[0,1] op_sel_hi:[1,0]
	v_add_f32_e32 v50, 0, v50
	v_add_f32_e32 v54, v38, v39
	v_add_f32_e32 v56, v40, v41
	v_mov_b32_e32 v51, v34
	v_mov_b32_e32 v53, v35
	v_mov_b32_e32 v55, v36
	v_mov_b32_e32 v57, v37
	v_pk_add_f32 v[50:51], v[50:51], v[52:53]
	v_pk_add_f32 v[52:53], v[54:55], v[56:57]
	s_nop 0
	v_pk_add_f32 v[50:51], v[50:51], v[52:53]
	v_add_f32_e32 v50, v50, v51
	v_mov_b32_e32 v51, v50
	s_nop 1
	v_add_f32_dpp v51, v51, v51 quad_perm:[1,0,3,2] row_mask:0xf bank_mask:0xf
	s_nop 1
	v_add_f32_dpp v51, v51, v51 quad_perm:[2,3,0,1] row_mask:0xf bank_mask:0xf
	s_nop 1
	v_add_f32_dpp v51, v51, v51 row_half_mirror row_mask:0xf bank_mask:0xf
	s_nop 1
	v_add_f32_dpp v51, v51, v51 row_mirror row_mask:0xf bank_mask:0xf
	s_nop 1
	v_add_f32_dpp v51, v51, v51 row_bcast:15 row_mask:0xa bank_mask:0xf
	s_nop 1
	v_add_f32_dpp v51, v51, v51 row_bcast:31 row_mask:0xc bank_mask:0xf
	s_nop 1
	v_readlane_b32 vcc_lo, v51, 63
	s_nop 1
	v_mov_b32_e32 v51, vcc_lo
	v_fmamk_f32 v49, v51, 0xba800000, v49
	v_fmamk_f32 v47, v51, 0xba800000, v47
	v_fmamk_f32 v48, v51, 0xba800000, v48
	v_fmac_f32_e32 v46, 0xba800000, v51
	v_mul_f32_e32 v50, v47, v47
	v_mul_f32_e32 v58, v49, v49
	v_fmac_f32_e32 v50, v46, v46
	v_fmac_f32_e32 v58, v48, v48
	v_fmamk_f32 v45, v51, 0xba800000, v45
	v_fmamk_f32 v43, v51, 0xba800000, v43
	v_add_f32_e32 v50, v50, v58
	v_fmamk_f32 v44, v51, 0xba800000, v44
	v_fmac_f32_e32 v42, 0xba800000, v51
	v_mul_f32_e32 v58, v43, v43
	v_mul_f32_e32 v59, v45, v45
	v_fmac_f32_e32 v58, v42, v42
	v_fmac_f32_e32 v59, v44, v44
	v_add_f32_e32 v58, v58, v59
	v_fmamk_f32 v41, v51, 0xba800000, v41
	v_fmamk_f32 v39, v51, 0xba800000, v39
	v_add_f32_e32 v50, v50, v58
	v_fmamk_f32 v40, v51, 0xba800000, v40
	v_fmac_f32_e32 v38, 0xba800000, v51
	v_mul_f32_e32 v58, v39, v39
	v_mul_f32_e32 v59, v41, v41
	v_fmac_f32_e32 v58, v38, v38
	v_fmac_f32_e32 v59, v40, v40
	v_add_f32_e32 v58, v58, v59
	v_fmamk_f32 v37, v51, 0xba800000, v37
	v_fmamk_f32 v35, v51, 0xba800000, v35
	v_add_f32_e32 v50, v50, v58
	v_fmamk_f32 v36, v51, 0xba800000, v36
	v_fmac_f32_e32 v34, 0xba800000, v51
	v_mul_f32_e32 v58, v35, v35
	v_mul_f32_e32 v59, v37, v37
	v_fmac_f32_e32 v58, v34, v34
	v_fmac_f32_e32 v59, v36, v36
	v_add_f32_e32 v58, v58, v59
	v_add_f32_e32 v50, v50, v58
	s_nop 1
	v_add_f32_dpp v50, v50, v50 quad_perm:[1,0,3,2] row_mask:0xf bank_mask:0xf
	s_nop 1
	v_add_f32_dpp v50, v50, v50 quad_perm:[2,3,0,1] row_mask:0xf bank_mask:0xf
	s_nop 1
	v_add_f32_dpp v50, v50, v50 row_half_mirror row_mask:0xf bank_mask:0xf
	s_nop 1
	v_add_f32_dpp v50, v50, v50 row_mirror row_mask:0xf bank_mask:0xf
	s_nop 1
	v_add_f32_dpp v50, v50, v50 row_bcast:15 row_mask:0xa bank_mask:0xf
	s_nop 1
	v_add_f32_dpp v50, v50, v50 row_bcast:31 row_mask:0xc bank_mask:0xf
	s_nop 1
	v_readlane_b32 vcc_lo, v50, 63
	s_nop 1
	v_mov_b32_e32 v50, vcc_lo
	v_fmamk_f32 v50, v50, 0x3a800000, v213
	v_mul_f32_e32 v52, 0x4f800000, v50
	v_cmp_gt_f32_e32 vcc, s61, v50
	s_nop 1
	v_cndmask_b32_e32 v50, v50, v52, vcc
	v_sqrt_f32_e32 v52, v50
	s_nop 0
	v_add_u32_e32 v53, -1, v52
	v_fma_f32 v54, -v53, v52, v50
	v_cmp_ge_f32_e64 s[0:1], 0, v54
	v_add_u32_e32 v54, 1, v52
	s_nop 0
	v_cndmask_b32_e64 v53, v52, v53, s[0:1]
	v_fma_f32 v52, -v54, v52, v50
	v_cmp_lt_f32_e64 s[0:1], 0, v52
	s_nop 1
	v_cndmask_b32_e64 v52, v53, v54, s[0:1]
	v_mul_f32_e32 v53, 0x37800000, v52
	v_cndmask_b32_e32 v52, v52, v53, vcc
	v_cmp_class_f32_e32 vcc, v50, v214
	s_nop 1
	v_cndmask_b32_e32 v50, v52, v50, vcc
	v_div_scale_f32 v52, s[0:1], v50, v50, 1.0
	v_rcp_f32_e32 v53, v52
	s_nop 0
	v_fma_f32 v54, -v52, v53, 1.0
	v_fmac_f32_e32 v53, v54, v53
	v_div_scale_f32 v54, vcc, 1.0, v50, 1.0
	v_mul_f32_e32 v55, v54, v53
	v_fma_f32 v56, -v52, v55, v54
	v_fmac_f32_e32 v55, v56, v53
	v_fma_f32 v52, -v52, v55, v54
	v_div_fmas_f32 v52, v52, v53, v55
	v_div_fixup_f32 v50, v52, v50, 1.0
	s_and_saveexec_b64 s[0:1], s[36:37]
	s_cbranch_execz .LBB0_171
	s_add_u32 s10, s90, s34
	v_mul_f32_e32 v52, 0x3a800000, v51
	s_addc_u32 s11, s91, s35
	v_mov_b32_e32 v53, v50
	global_store_dwordx2 v1, v[52:53], s[10:11]

.LBB0_172:
	s_min_i32 s0, s49, 0x8000
	s_ashr_i32 s0, s0, 12
	s_mulk_i32 s0, 0xc00
	s_ashr_i32 s1, s0, 31
	s_lshl_b64 s[0:1], s[0:1], 2
	s_add_u32 s0, s19, s0
	s_addc_u32 s1, s28, s1
	s_add_u32 s16, s0, 0x1000
	s_addc_u32 s17, s1, 0
	global_load_dwordx4 v[120:123], v0, s[0:1]
	global_load_dwordx4 v[124:127], v0, s[0:1] offset:1024
	global_load_dwordx4 v[128:131], v0, s[0:1] offset:2048
	global_load_dwordx4 v[132:135], v0, s[0:1] offset:3072
	global_load_dwordx4 v[136:139], v0, s[16:17]
	global_load_dwordx4 v[140:143], v0, s[16:17] offset:1024
	global_load_dwordx4 v[144:147], v0, s[16:17] offset:2048
	global_load_dwordx4 v[148:151], v0, s[16:17] offset:3072
	v_lshl_add_u64 v[60:61], s[90:91], 0, v[76:77]
	v_add_co_u32_e32 v60, vcc, s70, v60
	v_addc_co_u32_e32 v61, vcc, 0, v61, vcc
	s_waitcnt vmcnt(0)
	v_pk_add_f32 v[138:139], v[138:139], 1.0 op_sel_hi:[1,0]
	v_pk_add_f32 v[136:137], v[136:137], 1.0 op_sel_hi:[1,0]
	v_pk_fma_f32 v[48:49], v[48:49], v[138:139], v[122:123]
	v_pk_fma_f32 v[46:47], v[46:47], v[136:137], v[120:121]
	s_nop 0
	v_cvt_pk_bf16_f32 v46, v46, v47
	v_cvt_pk_bf16_f32 v47, v48, v49
	global_store_dwordx2 v[60:61], v[46:47], off
	v_pk_add_f32 v[142:143], v[142:143], 1.0 op_sel_hi:[1,0]
	v_pk_add_f32 v[140:141], v[140:141], 1.0 op_sel_hi:[1,0]
	v_pk_fma_f32 v[44:45], v[44:45], v[142:143], v[126:127]
	v_pk_fma_f32 v[42:43], v[42:43], v[140:141], v[124:125]
	s_nop 0
	v_cvt_pk_bf16_f32 v42, v42, v43
	v_cvt_pk_bf16_f32 v43, v44, v45
	global_store_dwordx2 v[60:61], v[42:43], off offset:512
	v_pk_add_f32 v[146:147], v[146:147], 1.0 op_sel_hi:[1,0]
	v_pk_add_f32 v[144:145], v[144:145], 1.0 op_sel_hi:[1,0]
	v_pk_fma_f32 v[40:41], v[40:41], v[146:147], v[130:131]
	v_pk_fma_f32 v[38:39], v[38:39], v[144:145], v[128:129]
	s_nop 0
	v_cvt_pk_bf16_f32 v38, v38, v39
	v_cvt_pk_bf16_f32 v39, v40, v41
	global_store_dwordx2 v[60:61], v[38:39], off offset:1024
	v_pk_add_f32 v[150:151], v[150:151], 1.0 op_sel_hi:[1,0]
	v_pk_add_f32 v[148:149], v[148:149], 1.0 op_sel_hi:[1,0]
	v_pk_fma_f32 v[36:37], v[36:37], v[150:151], v[134:135]
	v_pk_fma_f32 v[34:35], v[34:35], v[148:149], v[132:133]
	s_nop 0
	v_cvt_pk_bf16_f32 v34, v34, v35
	v_cvt_pk_bf16_f32 v35, v36, v37
	global_store_dwordx2 v[60:61], v[34:35], off offset:1536
	s_andn2_b64 vcc, exec, s[50:51]
	s_cbranch_vccnz .LBB0_162
	s_and_b64 vcc, exec, s[38:39]
	s_add_i32 s10, s31, s46
	s_cbranch_vccnz .LBB0_177
	v_mov_b32_e32 v34, v31
	v_mov_b32_e32 v35, v32
	v_mov_b32_e32 v36, v30
	v_mov_b32_e32 v37, v33
	v_pk_add_f32 v[34:35], v[34:35], v[36:37]
	v_mov_b32_e32 v36, v27
	v_mov_b32_e32 v37, v28
	v_mov_b32_e32 v38, v26
	v_mov_b32_e32 v39, v29
	v_pk_add_f32 v[36:37], v[36:37], v[38:39]
	v_add_f32_e32 v34, v34, v35
	v_pk_add_f32 v[36:37], v[36:37], v[36:37] op_sel:[0,1] op_sel_hi:[1,0]
	v_add_f32_e32 v34, 0, v34
	v_add_f32_e32 v38, v18, v19
	v_add_f32_e32 v40, v20, v21
	v_mov_b32_e32 v35, v22
	v_mov_b32_e32 v37, v23
	v_mov_b32_e32 v39, v24
	v_mov_b32_e32 v41, v25
	v_pk_add_f32 v[34:35], v[34:35], v[36:37]
	v_pk_add_f32 v[36:37], v[38:39], v[40:41]
	s_nop 0
	v_pk_add_f32 v[34:35], v[34:35], v[36:37]
	v_add_f32_e32 v34, v34, v35
	v_mov_b32_e32 v35, v34
	s_nop 1
	v_add_f32_dpp v35, v35, v35 quad_perm:[1,0,3,2] row_mask:0xf bank_mask:0xf
	s_nop 1
	v_add_f32_dpp v35, v35, v35 quad_perm:[2,3,0,1] row_mask:0xf bank_mask:0xf
	s_nop 1
	v_add_f32_dpp v35, v35, v35 row_half_mirror row_mask:0xf bank_mask:0xf
	s_nop 1
	v_add_f32_dpp v35, v35, v35 row_mirror row_mask:0xf bank_mask:0xf
	s_nop 1
	v_add_f32_dpp v35, v35, v35 row_bcast:15 row_mask:0xa bank_mask:0xf
	s_nop 1
	v_add_f32_dpp v35, v35, v35 row_bcast:31 row_mask:0xc bank_mask:0xf
	s_nop 1
	v_readlane_b32 vcc_lo, v35, 63
	s_nop 1
	v_mov_b32_e32 v35, vcc_lo
	v_fmamk_f32 v33, v35, 0xba800000, v33
	v_fmamk_f32 v31, v35, 0xba800000, v31
	v_fmamk_f32 v32, v35, 0xba800000, v32
	v_fmac_f32_e32 v30, 0xba800000, v35
	v_mul_f32_e32 v34, v31, v31
	v_mul_f32_e32 v42, v33, v33
	v_fmac_f32_e32 v34, v30, v30
	v_fmac_f32_e32 v42, v32, v32
	v_fmamk_f32 v29, v35, 0xba800000, v29
	v_fmamk_f32 v27, v35, 0xba800000, v27
	v_add_f32_e32 v34, v34, v42
	v_fmamk_f32 v28, v35, 0xba800000, v28
	v_fmac_f32_e32 v26, 0xba800000, v35
	v_mul_f32_e32 v42, v27, v27
	v_mul_f32_e32 v43, v29, v29
	v_fmac_f32_e32 v42, v26, v26
	v_fmac_f32_e32 v43, v28, v28
	v_add_f32_e32 v42, v42, v43
	v_fmamk_f32 v21, v35, 0xba800000, v21
	v_fmamk_f32 v19, v35, 0xba800000, v19
	v_add_f32_e32 v34, v34, v42
	v_fmamk_f32 v20, v35, 0xba800000, v20
	v_fmac_f32_e32 v18, 0xba800000, v35
	v_mul_f32_e32 v42, v19, v19
	v_mul_f32_e32 v43, v21, v21
	v_fmac_f32_e32 v42, v18, v18
	v_fmac_f32_e32 v43, v20, v20
	v_add_f32_e32 v42, v42, v43
	v_fmamk_f32 v25, v35, 0xba800000, v25
	v_fmamk_f32 v23, v35, 0xba800000, v23
	v_add_f32_e32 v34, v34, v42
	v_fmamk_f32 v24, v35, 0xba800000, v24
	v_fmac_f32_e32 v22, 0xba800000, v35
	v_mul_f32_e32 v42, v23, v23
	v_mul_f32_e32 v43, v25, v25
	v_fmac_f32_e32 v42, v22, v22
	v_fmac_f32_e32 v43, v24, v24
	v_add_f32_e32 v42, v42, v43
	v_add_f32_e32 v34, v34, v42
	s_nop 1
	v_add_f32_dpp v34, v34, v34 quad_perm:[1,0,3,2] row_mask:0xf bank_mask:0xf
	s_nop 1
	v_add_f32_dpp v34, v34, v34 quad_perm:[2,3,0,1] row_mask:0xf bank_mask:0xf
	s_nop 1
	v_add_f32_dpp v34, v34, v34 row_half_mirror row_mask:0xf bank_mask:0xf
	s_nop 1
	v_add_f32_dpp v34, v34, v34 row_mirror row_mask:0xf bank_mask:0xf
	s_nop 1
	v_add_f32_dpp v34, v34, v34 row_bcast:15 row_mask:0xa bank_mask:0xf
	s_nop 1
	v_add_f32_dpp v34, v34, v34 row_bcast:31 row_mask:0xc bank_mask:0xf
	s_nop 1
	v_readlane_b32 vcc_lo, v34, 63
	s_nop 1
	v_mov_b32_e32 v34, vcc_lo
	v_fmamk_f32 v34, v34, 0x3a800000, v213
	v_mul_f32_e32 v36, 0x4f800000, v34
	v_cmp_gt_f32_e32 vcc, s61, v34
	s_nop 1
	v_cndmask_b32_e32 v34, v34, v36, vcc
	v_sqrt_f32_e32 v36, v34
	s_nop 0
	v_add_u32_e32 v37, -1, v36
	v_fma_f32 v38, -v37, v36, v34
	v_cmp_ge_f32_e64 s[0:1], 0, v38
	v_add_u32_e32 v38, 1, v36
	s_nop 0
	v_cndmask_b32_e64 v37, v36, v37, s[0:1]
	v_fma_f32 v36, -v38, v36, v34
	v_cmp_lt_f32_e64 s[0:1], 0, v36
	s_nop 1
	v_cndmask_b32_e64 v36, v37, v38, s[0:1]
	v_mul_f32_e32 v37, 0x37800000, v36
	v_cndmask_b32_e32 v36, v36, v37, vcc
	v_cmp_class_f32_e32 vcc, v34, v214
	s_nop 1
	v_cndmask_b32_e32 v34, v36, v34, vcc
	v_div_scale_f32 v36, s[0:1], v34, v34, 1.0
	v_rcp_f32_e32 v37, v36
	s_nop 0
	v_fma_f32 v38, -v36, v37, 1.0
	v_fmac_f32_e32 v37, v38, v37
	v_div_scale_f32 v38, vcc, 1.0, v34, 1.0
	v_mul_f32_e32 v39, v38, v37
	v_fma_f32 v40, -v36, v39, v38
	v_fmac_f32_e32 v39, v40, v37
	v_fma_f32 v36, -v36, v39, v38
	v_div_fmas_f32 v36, v36, v37, v39
	v_div_fixup_f32 v34, v36, v34, 1.0
	s_and_saveexec_b64 s[0:1], s[36:37]
	s_cbranch_execz .LBB0_176
	s_ashr_i32 s11, s10, 31
	s_lshl_b64 s[50:51], s[10:11], 3
	v_readlane_b32 s11, v252, 20
	s_add_u32 s50, s11, s50
	v_readlane_b32 s11, v252, 21
	v_mul_f32_e32 v36, 0x3a800000, v35
	s_addc_u32 s51, s11, s51
	v_mov_b32_e32 v37, v34
	global_store_dwordx2 v1, v[36:37], s[50:51]

.LBB0_177:
	s_min_i32 s0, s10, 0x8000
	s_ashr_i32 s0, s0, 12
	s_mulk_i32 s0, 0xc00
	s_ashr_i32 s1, s0, 31
	s_lshl_b64 s[0:1], s[0:1], 2
	s_add_u32 s0, s19, s0
	s_addc_u32 s1, s28, s1
	s_add_u32 s16, s0, 0x1000
	s_addc_u32 s17, s1, 0
	global_load_dwordx4 v[120:123], v0, s[0:1]
	global_load_dwordx4 v[124:127], v0, s[0:1] offset:1024
	global_load_dwordx4 v[128:131], v0, s[0:1] offset:2048
	global_load_dwordx4 v[132:135], v0, s[0:1] offset:3072
	global_load_dwordx4 v[136:139], v0, s[16:17]
	global_load_dwordx4 v[140:143], v0, s[16:17] offset:1024
	global_load_dwordx4 v[144:147], v0, s[16:17] offset:2048
	global_load_dwordx4 v[148:151], v0, s[16:17] offset:3072
	s_ashr_i32 s11, s10, 31
	s_lshl_b64 s[10:11], s[10:11], 11
	v_lshl_add_u64 v[42:43], v[72:73], 0, s[10:11]
	s_waitcnt vmcnt(0)
	v_pk_add_f32 v[138:139], v[138:139], 1.0 op_sel_hi:[1,0]
	v_pk_add_f32 v[136:137], v[136:137], 1.0 op_sel_hi:[1,0]
	v_pk_fma_f32 v[32:33], v[32:33], v[138:139], v[122:123]
	v_pk_fma_f32 v[30:31], v[30:31], v[136:137], v[120:121]
	s_nop 0
	v_cvt_pk_bf16_f32 v30, v30, v31
	v_cvt_pk_bf16_f32 v31, v32, v33
	global_store_dwordx2 v[42:43], v[30:31], off
	v_pk_add_f32 v[142:143], v[142:143], 1.0 op_sel_hi:[1,0]
	v_pk_add_f32 v[140:141], v[140:141], 1.0 op_sel_hi:[1,0]
	v_pk_fma_f32 v[28:29], v[28:29], v[142:143], v[126:127]
	v_pk_fma_f32 v[26:27], v[26:27], v[140:141], v[124:125]
	s_nop 0
	v_cvt_pk_bf16_f32 v26, v26, v27
	v_cvt_pk_bf16_f32 v27, v28, v29
	global_store_dwordx2 v[42:43], v[26:27], off offset:512
	v_pk_add_f32 v[146:147], v[146:147], 1.0 op_sel_hi:[1,0]
	v_pk_add_f32 v[144:145], v[144:145], 1.0 op_sel_hi:[1,0]
	v_pk_fma_f32 v[20:21], v[20:21], v[146:147], v[130:131]
	v_pk_fma_f32 v[18:19], v[18:19], v[144:145], v[128:129]
	s_nop 0
	v_cvt_pk_bf16_f32 v18, v18, v19
	v_cvt_pk_bf16_f32 v19, v20, v21
	global_store_dwordx2 v[42:43], v[18:19], off offset:1024
	v_pk_add_f32 v[150:151], v[150:151], 1.0 op_sel_hi:[1,0]
	v_pk_add_f32 v[148:149], v[148:149], 1.0 op_sel_hi:[1,0]
	v_pk_fma_f32 v[24:25], v[24:25], v[150:151], v[134:135]
	v_pk_fma_f32 v[22:23], v[22:23], v[148:149], v[132:133]
	s_nop 0
	v_cvt_pk_bf16_f32 v22, v22, v23
	v_cvt_pk_bf16_f32 v23, v24, v25
	global_store_dwordx2 v[42:43], v[22:23], off offset:1536
	s_andn2_b64 vcc, exec, s[8:9]
	s_cbranch_vccnz .LBB0_162
	s_mul_i32 s0, s12, 3
	s_and_b64 vcc, exec, s[38:39]
	s_add_i32 s8, s0, s46
	s_cbranch_vccnz .LBB0_161
	v_mov_b32_e32 v18, v15
	v_mov_b32_e32 v19, v16
	v_mov_b32_e32 v20, v14
	v_mov_b32_e32 v21, v17
	v_pk_add_f32 v[18:19], v[18:19], v[20:21]
	v_mov_b32_e32 v20, v11
	v_mov_b32_e32 v21, v12
	v_mov_b32_e32 v22, v10
	v_mov_b32_e32 v23, v13
	v_pk_add_f32 v[20:21], v[20:21], v[22:23]
	v_add_f32_e32 v18, v18, v19
	v_pk_add_f32 v[20:21], v[20:21], v[20:21] op_sel:[0,1] op_sel_hi:[1,0]
	v_add_f32_e32 v18, 0, v18
	v_add_f32_e32 v22, v2, v3
	v_add_f32_e32 v24, v4, v5
	v_mov_b32_e32 v19, v6
	v_mov_b32_e32 v21, v7
	v_mov_b32_e32 v23, v8
	v_mov_b32_e32 v25, v9
	v_pk_add_f32 v[18:19], v[18:19], v[20:21]
	v_pk_add_f32 v[20:21], v[22:23], v[24:25]
	s_nop 0
	v_pk_add_f32 v[18:19], v[18:19], v[20:21]
	v_add_f32_e32 v18, v18, v19
	v_mov_b32_e32 v19, v18
	s_nop 1
	v_add_f32_dpp v19, v19, v19 quad_perm:[1,0,3,2] row_mask:0xf bank_mask:0xf
	s_nop 1
	v_add_f32_dpp v19, v19, v19 quad_perm:[2,3,0,1] row_mask:0xf bank_mask:0xf
	s_nop 1
	v_add_f32_dpp v19, v19, v19 row_half_mirror row_mask:0xf bank_mask:0xf
	s_nop 1
	v_add_f32_dpp v19, v19, v19 row_mirror row_mask:0xf bank_mask:0xf
	s_nop 1
	v_add_f32_dpp v19, v19, v19 row_bcast:15 row_mask:0xa bank_mask:0xf
	s_nop 1
	v_add_f32_dpp v19, v19, v19 row_bcast:31 row_mask:0xc bank_mask:0xf
	s_nop 1
	v_readlane_b32 vcc_lo, v19, 63
	s_nop 1
	v_mov_b32_e32 v19, vcc_lo
	v_fmamk_f32 v17, v19, 0xba800000, v17
	v_fmamk_f32 v15, v19, 0xba800000, v15
	v_fmamk_f32 v16, v19, 0xba800000, v16
	v_fmac_f32_e32 v14, 0xba800000, v19
	v_mul_f32_e32 v18, v15, v15
	v_mul_f32_e32 v26, v17, v17
	v_fmac_f32_e32 v18, v14, v14
	v_fmac_f32_e32 v26, v16, v16
	v_fmamk_f32 v13, v19, 0xba800000, v13
	v_fmamk_f32 v11, v19, 0xba800000, v11
	v_add_f32_e32 v18, v18, v26
	v_fmamk_f32 v12, v19, 0xba800000, v12
	v_fmac_f32_e32 v10, 0xba800000, v19
	v_mul_f32_e32 v26, v11, v11
	v_mul_f32_e32 v27, v13, v13
	v_fmac_f32_e32 v26, v10, v10
	v_fmac_f32_e32 v27, v12, v12
	v_add_f32_e32 v26, v26, v27
	v_fmamk_f32 v5, v19, 0xba800000, v5
	v_fmamk_f32 v3, v19, 0xba800000, v3
	v_add_f32_e32 v18, v18, v26
	v_fmamk_f32 v4, v19, 0xba800000, v4
	v_fmac_f32_e32 v2, 0xba800000, v19
	v_mul_f32_e32 v26, v3, v3
	v_mul_f32_e32 v27, v5, v5
	v_fmac_f32_e32 v26, v2, v2
	v_fmac_f32_e32 v27, v4, v4
	v_add_f32_e32 v26, v26, v27
	v_fmamk_f32 v9, v19, 0xba800000, v9
	v_fmamk_f32 v7, v19, 0xba800000, v7
	v_add_f32_e32 v18, v18, v26
	v_fmamk_f32 v8, v19, 0xba800000, v8
	v_fmac_f32_e32 v6, 0xba800000, v19
	v_mul_f32_e32 v26, v7, v7
	v_mul_f32_e32 v27, v9, v9
	v_fmac_f32_e32 v26, v6, v6
	v_fmac_f32_e32 v27, v8, v8
	v_add_f32_e32 v26, v26, v27
	v_add_f32_e32 v18, v18, v26
	s_nop 1
	v_add_f32_dpp v18, v18, v18 quad_perm:[1,0,3,2] row_mask:0xf bank_mask:0xf
	s_nop 1
	v_add_f32_dpp v18, v18, v18 quad_perm:[2,3,0,1] row_mask:0xf bank_mask:0xf
	s_nop 1
	v_add_f32_dpp v18, v18, v18 row_half_mirror row_mask:0xf bank_mask:0xf
	s_nop 1
	v_add_f32_dpp v18, v18, v18 row_mirror row_mask:0xf bank_mask:0xf
	s_nop 1
	v_add_f32_dpp v18, v18, v18 row_bcast:15 row_mask:0xa bank_mask:0xf
	s_nop 1
	v_add_f32_dpp v18, v18, v18 row_bcast:31 row_mask:0xc bank_mask:0xf
	s_nop 1
	v_readlane_b32 vcc_lo, v18, 63
	s_nop 1
	v_mov_b32_e32 v18, vcc_lo
	v_fmamk_f32 v18, v18, 0x3a800000, v213
	v_mul_f32_e32 v20, 0x4f800000, v18
	v_cmp_gt_f32_e32 vcc, s61, v18
	s_nop 1
	v_cndmask_b32_e32 v18, v18, v20, vcc
	v_sqrt_f32_e32 v20, v18
	s_nop 0
	v_add_u32_e32 v21, -1, v20
	v_fma_f32 v22, -v21, v20, v18
	v_cmp_ge_f32_e64 s[0:1], 0, v22
	v_add_u32_e32 v22, 1, v20
	s_nop 0
	v_cndmask_b32_e64 v21, v20, v21, s[0:1]
	v_fma_f32 v20, -v22, v20, v18
	v_cmp_lt_f32_e64 s[0:1], 0, v20
	s_nop 1
	v_cndmask_b32_e64 v20, v21, v22, s[0:1]
	v_mul_f32_e32 v21, 0x37800000, v20
	v_cndmask_b32_e32 v20, v20, v21, vcc
	v_cmp_class_f32_e32 vcc, v18, v214
	s_nop 1
	v_cndmask_b32_e32 v18, v20, v18, vcc
	v_div_scale_f32 v20, s[0:1], v18, v18, 1.0
	v_rcp_f32_e32 v21, v20
	s_nop 0
	v_fma_f32 v22, -v20, v21, 1.0
	v_fmac_f32_e32 v21, v22, v21
	v_div_scale_f32 v22, vcc, 1.0, v18, 1.0
	v_mul_f32_e32 v23, v22, v21
	v_fma_f32 v24, -v20, v23, v22
	v_fmac_f32_e32 v23, v24, v21
	v_fma_f32 v20, -v20, v23, v22
	v_div_fmas_f32 v20, v20, v21, v23
	v_div_fixup_f32 v18, v20, v18, 1.0
	s_and_saveexec_b64 s[0:1], s[36:37]
	s_cbranch_execz .LBB0_160
	s_ashr_i32 s9, s8, 31
	s_lshl_b64 s[10:11], s[8:9], 3
	v_readlane_b32 s9, v252, 20
	s_add_u32 s10, s9, s10
	v_readlane_b32 s9, v252, 21
	v_mul_f32_e32 v20, 0x3a800000, v19
	s_addc_u32 s11, s9, s11
	v_mov_b32_e32 v21, v18
	global_store_dwordx2 v1, v[20:21], s[10:11]
	s_branch .LBB0_160

.LBB0_717:
	s_add_i32 s10, s96, s48
	s_cmp_lt_i32 s10, 0x8000
	s_cselect_b32 s0, s10, s48
	s_ashr_i32 s1, s0, 31
	s_lshl_b64 s[12:13], s[0:1], 12
	s_add_i32 s6, s97, s48
	s_cmp_lt_i32 s6, 0x8000
	s_cselect_b64 s[8:9], -1, 0
	s_and_b64 s[0:1], s[8:9], exec
	s_cselect_b32 s0, s6, s48
	s_ashr_i32 s1, s0, 31
	s_lshl_b64 s[14:15], s[0:1], 12
	s_add_i32 s2, s17, s48
	s_cmp_lt_i32 s2, 0x8000
	s_cselect_b64 s[4:5], -1, 0
	s_and_b64 s[0:1], s[4:5], exec
	s_cselect_b32 s0, s2, s48
	s_ashr_i32 s49, s48, 31
	s_lshl_b64 s[20:21], s[48:49], 12
	v_lshl_add_u64 v[58:59], v[52:53], 0, s[20:21]
	global_load_dwordx4 v[10:13], v[58:59], off nt
	global_load_dwordx4 v[2:5], v[58:59], off offset:1024 nt
	global_load_dwordx4 v[48:51], v[58:59], off offset:2048 nt
	global_load_dwordx4 v[44:47], v[58:59], off offset:3072 nt
	s_nop 0
	s_nop 0
	s_ashr_i32 s1, s0, 31
	s_lshl_b64 s[0:1], s[0:1], 12
	v_lshl_add_u64 v[84:85], v[52:53], 0, s[0:1]
	v_lshl_add_u64 v[80:81], v[52:53], 0, s[12:13]
	v_lshl_add_u64 v[82:83], v[52:53], 0, s[14:15]
	global_load_dwordx4 v[36:39], v[80:81], off nt
	global_load_dwordx4 v[32:35], v[80:81], off offset:1024 nt
	s_cmpk_gt_i32 s10, 0x7fff
	s_waitcnt vmcnt(2)
	v_mov_b32_e32 v0, v11
	v_mov_b32_e32 v1, v12
	v_mov_b32_e32 v6, v10
	v_mov_b32_e32 v7, v13
	v_mov_b32_e32 v8, v3
	v_mov_b32_e32 v9, v4
	v_mov_b32_e32 v14, v2
	v_mov_b32_e32 v15, v5
	v_pk_add_f32 v[0:1], v[0:1], v[6:7]
	v_pk_add_f32 v[6:7], v[8:9], v[14:15]
	v_add_f32_e32 v14, v0, v1
	v_pk_add_f32 v[0:1], v[6:7], v[6:7] op_sel:[0,1] op_sel_hi:[1,0]
	v_add_f32_e32 v16, v48, v49
	v_add_f32_e32 v18, v50, v51
	v_mov_b32_e32 v21, v44
	v_mov_b32_e32 v17, v46
	v_mov_b32_e32 v19, v47
	v_add_f32_e32 v20, 0, v14
	v_mov_b32_e32 v1, v45
	v_pk_add_f32 v[8:9], v[16:17], v[18:19]
	v_pk_add_f32 v[0:1], v[20:21], v[0:1]
	s_nop 0
	v_pk_add_f32 v[0:1], v[0:1], v[8:9]
	s_nop 0
	v_add_f32_e32 v0, v0, v1
	s_nop 1
	v_add_f32_dpp v0, v0, v0 quad_perm:[1,0,3,2] row_mask:0xf bank_mask:0xf
	s_nop 1
	v_add_f32_dpp v0, v0, v0 quad_perm:[2,3,0,1] row_mask:0xf bank_mask:0xf
	s_nop 1
	v_add_f32_dpp v0, v0, v0 row_half_mirror row_mask:0xf bank_mask:0xf
	s_nop 1
	v_add_f32_dpp v0, v0, v0 row_mirror row_mask:0xf bank_mask:0xf
	s_nop 1
	v_add_f32_dpp v0, v0, v0 row_bcast:15 row_mask:0xa bank_mask:0xf
	s_nop 1
	v_add_f32_dpp v0, v0, v0 row_bcast:31 row_mask:0xc bank_mask:0xf
	s_nop 1
	v_readlane_b32 vcc_lo, v0, 63
	s_nop 1
	v_mov_b32_e32 v0, vcc_lo
	v_fmamk_f32 v7, v0, 0xba800000, v11
	v_fmamk_f32 v6, v0, 0xba800000, v10
	v_fmamk_f32 v13, v0, 0xba800000, v13
	v_fmac_f32_e32 v12, 0xba800000, v0
	v_fmamk_f32 v41, v0, 0xba800000, v3
	v_fmamk_f32 v40, v0, 0xba800000, v2
	v_fmamk_f32 v5, v0, 0xba800000, v5
	v_fmac_f32_e32 v4, 0xba800000, v0
	v_fmamk_f32 v77, v0, 0xba800000, v49
	v_fmamk_f32 v76, v0, 0xba800000, v48
	v_fmamk_f32 v51, v0, 0xba800000, v51
	v_fmac_f32_e32 v50, 0xba800000, v0
	v_fmamk_f32 v79, v0, 0xba800000, v47
	v_fmamk_f32 v78, v0, 0xba800000, v46
	v_fmamk_f32 v45, v0, 0xba800000, v45
	v_fmac_f32_e32 v44, 0xba800000, v0
	v_pk_mul_f32 v[0:1], v[12:13], v[12:13]
	v_pk_mul_f32 v[2:3], v[6:7], v[6:7]
	v_pk_mul_f32 v[8:9], v[4:5], v[4:5]
	v_pk_mul_f32 v[10:11], v[40:41], v[40:41]
	v_pk_mov_b32 v[18:19], v[2:3], v[0:1] op_sel:[1,0]
	v_mov_b32_e32 v3, v1
	v_pk_mov_b32 v[0:1], v[10:11], v[8:9] op_sel:[1,0]
	v_mov_b32_e32 v11, v9
	v_mul_f32_e32 v17, v44, v44
	v_mul_f32_e32 v14, v77, v77
	v_mul_f32_e32 v16, v51, v51
	v_pk_add_f32 v[2:3], v[18:19], v[2:3]
	v_pk_add_f32 v[0:1], v[0:1], v[10:11]
	v_mul_f32_e32 v20, v45, v45
	v_mul_f32_e32 v21, v78, v78
	v_mul_f32_e32 v22, v79, v79
	v_pk_fma_f32 v[8:9], v[76:77], v[76:77], v[14:15] op_sel_hi:[1,1,0]
	v_pk_fma_f32 v[14:15], v[50:51], v[50:51], v[16:17] op_sel_hi:[1,1,0]
	v_pk_add_f32 v[2:3], v[2:3], v[2:3] op_sel:[0,1] op_sel_hi:[1,0]
	v_pk_add_f32 v[0:1], v[0:1], v[0:1] op_sel:[0,1] op_sel_hi:[1,0]
	v_mov_b32_e32 v9, v21
	v_mov_b32_e32 v15, v22
	v_mov_b32_e32 v3, v17
	v_mov_b32_e32 v1, v20
	v_pk_add_f32 v[8:9], v[8:9], v[14:15]
	v_pk_add_f32 v[0:1], v[2:3], v[0:1]
	global_load_dwordx4 v[20:23], v[82:83], off nt
	global_load_dwordx4 v[16:19], v[82:83], off offset:1024 nt
	v_pk_add_f32 v[0:1], v[0:1], v[8:9]
	s_nop 0
	v_add_f32_e32 v0, v0, v1
	s_nop 1
	v_add_f32_dpp v0, v0, v0 quad_perm:[1,0,3,2] row_mask:0xf bank_mask:0xf
	s_nop 1
	v_add_f32_dpp v0, v0, v0 quad_perm:[2,3,0,1] row_mask:0xf bank_mask:0xf
	s_nop 1
	v_add_f32_dpp v0, v0, v0 row_half_mirror row_mask:0xf bank_mask:0xf
	s_nop 1
	v_add_f32_dpp v0, v0, v0 row_mirror row_mask:0xf bank_mask:0xf
	s_nop 1
	v_add_f32_dpp v0, v0, v0 row_bcast:15 row_mask:0xa bank_mask:0xf
	s_nop 1
	v_add_f32_dpp v0, v0, v0 row_bcast:31 row_mask:0xc bank_mask:0xf
	s_nop 1
	v_readlane_b32 vcc_lo, v0, 63
	s_nop 1
	v_mov_b32_e32 v0, vcc_lo
	v_fmamk_f32 v0, v0, 0x3a800000, v66
	v_mul_f32_e32 v1, 0x4f800000, v0
	v_cmp_gt_f32_e32 vcc, s18, v0
	s_nop 1
	v_cndmask_b32_e32 v0, v0, v1, vcc
	v_sqrt_f32_e32 v1, v0
	s_nop 0
	v_add_u32_e32 v2, -1, v1
	v_add_u32_e32 v3, 1, v1
	v_fma_f32 v8, -v2, v1, v0
	v_fma_f32 v9, -v3, v1, v0
	v_cmp_ge_f32_e64 s[0:1], 0, v8
	s_nop 1
	v_cndmask_b32_e64 v1, v1, v2, s[0:1]
	v_cmp_lt_f32_e64 s[0:1], 0, v9
	s_nop 1
	v_cndmask_b32_e64 v1, v1, v3, s[0:1]
	v_mul_f32_e32 v2, 0x37800000, v1
	v_cndmask_b32_e32 v1, v1, v2, vcc
	v_cmp_class_f32_e32 vcc, v0, v67
	s_nop 1
	v_cndmask_b32_e32 v14, v1, v0, vcc
	v_div_scale_f32 v15, s[0:1], v14, v14, 1.0
	v_rcp_f32_e32 v42, v15
	v_div_scale_f32 v43, vcc, 1.0, v14, 1.0
	global_load_dwordx4 v[8:11], v[84:85], off nt
	global_load_dwordx4 v[0:3], v[84:85], off offset:1024 nt
	v_fma_f32 v46, -v15, v42, 1.0
	v_fmac_f32_e32 v42, v46, v42
	v_mul_f32_e32 v46, v43, v42
	v_fma_f32 v47, -v15, v46, v43
	v_fmac_f32_e32 v46, v47, v42
	v_fma_f32 v15, -v15, v46, v43
	v_div_fmas_f32 v15, v15, v42, v46
	v_div_fixup_f32 v86, v15, v14, 1.0
	v_pk_mul_f32 v[6:7], v[86:87], v[6:7] op_sel_hi:[0,1]
	v_pk_mul_f32 v[12:13], v[86:87], v[12:13] op_sel_hi:[0,1]
	v_pk_fma_f32 v[14:15], v[154:155], v[12:13], v[170:171]
	v_pk_fma_f32 v[12:13], v[152:153], v[6:7], v[168:169]
	global_store_dwordx4 v[58:59], v[12:15], off nt
	s_nop 0
	s_nop 0
	s_nop 0
	v_pk_mul_f32 v[6:7], v[86:87], v[4:5] op_sel_hi:[0,1]
	v_pk_mul_f32 v[4:5], v[86:87], v[40:41] op_sel_hi:[0,1]
	v_pk_mul_f32 v[50:51], v[86:87], v[50:51] op_sel_hi:[0,1]
	v_pk_mul_f32 v[76:77], v[86:87], v[76:77] op_sel_hi:[0,1]
	v_pk_mul_f32 v[44:45], v[86:87], v[44:45] op_sel_hi:[0,1]
	s_nop 0
	v_pk_fma_f32 v[4:5], v[156:157], v[4:5], v[172:173]
	v_pk_fma_f32 v[6:7], v[158:159], v[6:7], v[174:175]
	global_store_dwordx4 v[58:59], v[4:7], off offset:1024 nt
	s_nop 0
	s_nop 0
	global_load_dwordx4 v[46:49], v[80:81], off offset:2048 nt
	global_load_dwordx4 v[40:43], v[80:81], off offset:3072 nt
	global_load_dwordx4 v[28:31], v[82:83], off offset:2048 nt
	global_load_dwordx4 v[24:27], v[82:83], off offset:3072 nt
	global_load_dwordx4 v[12:15], v[84:85], off offset:2048 nt
	global_load_dwordx4 v[4:7], v[84:85], off offset:3072 nt
	s_nop 0
	v_pk_fma_f32 v[68:69], v[160:161], v[76:77], v[176:177]
	v_pk_fma_f32 v[70:71], v[162:163], v[50:51], v[178:179]
	global_store_dwordx4 v[58:59], v[68:71], off offset:2048 nt
	s_nop 0
	s_nop 0
	s_nop 0
	v_pk_mul_f32 v[50:51], v[86:87], v[78:79] op_sel_hi:[0,1]
	s_waitcnt vmcnt(5)
	v_pk_fma_f32 v[68:69], v[164:165], v[44:45], v[180:181]
	v_pk_fma_f32 v[70:71], v[166:167], v[50:51], v[182:183]
	global_store_dwordx4 v[58:59], v[68:71], off offset:3072 nt
	s_cbranch_scc1 .LBB0_716
	v_mov_b32_e32 v44, v37
	v_mov_b32_e32 v45, v38
	v_mov_b32_e32 v50, v36
	v_mov_b32_e32 v51, v39
	v_pk_add_f32 v[44:45], v[44:45], v[50:51]
	v_mov_b32_e32 v50, v33
	v_mov_b32_e32 v51, v34
	v_mov_b32_e32 v58, v32
	v_mov_b32_e32 v59, v35
	v_pk_add_f32 v[50:51], v[50:51], v[58:59]
	v_add_f32_e32 v44, v44, v45
	v_pk_add_f32 v[50:51], v[50:51], v[50:51] op_sel:[0,1] op_sel_hi:[1,0]
	v_add_f32_e32 v44, 0, v44
	v_add_f32_e32 v58, v46, v47
	v_add_f32_e32 v68, v48, v49
	v_mov_b32_e32 v45, v40
	v_mov_b32_e32 v51, v41
	v_mov_b32_e32 v59, v42
	v_mov_b32_e32 v69, v43
	v_pk_add_f32 v[44:45], v[44:45], v[50:51]
	v_pk_add_f32 v[50:51], v[58:59], v[68:69]
	s_ashr_i32 s11, s10, 31
	v_pk_add_f32 v[44:45], v[44:45], v[50:51]
	s_nop 0
	v_add_f32_e32 v44, v44, v45
	v_mov_b32_e32 v70, v44
	s_nop 1
	v_add_f32_dpp v70, v70, v70 quad_perm:[1,0,3,2] row_mask:0xf bank_mask:0xf
	s_nop 1
	v_add_f32_dpp v70, v70, v70 quad_perm:[2,3,0,1] row_mask:0xf bank_mask:0xf
	s_nop 1
	v_add_f32_dpp v70, v70, v70 row_half_mirror row_mask:0xf bank_mask:0xf
	s_nop 1
	v_add_f32_dpp v70, v70, v70 row_mirror row_mask:0xf bank_mask:0xf
	s_nop 1
	v_add_f32_dpp v70, v70, v70 row_bcast:15 row_mask:0xa bank_mask:0xf
	s_nop 1
	v_add_f32_dpp v70, v70, v70 row_bcast:31 row_mask:0xc bank_mask:0xf
	s_nop 1
	v_readlane_b32 vcc_lo, v70, 63
	s_nop 1
	v_mov_b32_e32 v70, vcc_lo
	v_fmamk_f32 v37, v70, 0xba800000, v37
	v_fmamk_f32 v36, v70, 0xba800000, v36
	v_fmamk_f32 v39, v70, 0xba800000, v39
	v_fmac_f32_e32 v38, 0xba800000, v70
	v_pk_mul_f32 v[44:45], v[38:39], v[38:39]
	v_pk_mul_f32 v[50:51], v[36:37], v[36:37]
	v_fmamk_f32 v33, v70, 0xba800000, v33
	v_fmamk_f32 v32, v70, 0xba800000, v32
	v_fmamk_f32 v35, v70, 0xba800000, v35
	v_pk_mov_b32 v[58:59], v[50:51], v[44:45] op_sel:[1,0]
	v_mov_b32_e32 v51, v45
	v_fmac_f32_e32 v34, 0xba800000, v70
	v_pk_add_f32 v[44:45], v[58:59], v[50:51]
	v_pk_mul_f32 v[50:51], v[34:35], v[34:35]
	v_pk_mul_f32 v[58:59], v[32:33], v[32:33]
	v_fmamk_f32 v41, v70, 0xba800000, v41
	v_pk_mov_b32 v[68:69], v[58:59], v[50:51] op_sel:[1,0]
	v_mov_b32_e32 v59, v51
	v_pk_add_f32 v[50:51], v[68:69], v[58:59]
	v_fmac_f32_e32 v40, 0xba800000, v70
	v_fmamk_f32 v59, v70, 0xba800000, v43
	v_fmamk_f32 v58, v70, 0xba800000, v42
	v_mul_f32_e32 v68, v40, v40
	v_mul_f32_e32 v69, v41, v41
	v_pk_add_f32 v[42:43], v[44:45], v[44:45] op_sel:[0,1] op_sel_hi:[1,0]
	v_pk_add_f32 v[44:45], v[50:51], v[50:51] op_sel:[0,1] op_sel_hi:[1,0]
	v_fmamk_f32 v47, v70, 0xba800000, v47
	v_mov_b32_e32 v43, v68
	v_mov_b32_e32 v45, v69
	v_fmamk_f32 v46, v70, 0xba800000, v46
	v_fmamk_f32 v49, v70, 0xba800000, v49
	v_pk_add_f32 v[50:51], v[42:43], v[44:45]
	v_mul_f32_e32 v42, v47, v47
	v_fmac_f32_e32 v48, 0xba800000, v70
	v_mul_f32_e32 v70, v58, v58
	v_pk_fma_f32 v[72:73], v[46:47], v[46:47], v[42:43] op_sel_hi:[1,1,0]
	v_mul_f32_e32 v42, v49, v49
	v_mov_b32_e32 v73, v70
	v_pk_fma_f32 v[74:75], v[48:49], v[48:49], v[42:43] op_sel_hi:[1,1,0]
	s_nop 0
	s_nop 0
	v_mul_f32_e32 v76, v59, v59
	v_mov_b32_e32 v75, v76
	v_pk_add_f32 v[72:73], v[72:73], v[74:75]
	s_nop 0
	v_pk_add_f32 v[50:51], v[50:51], v[72:73]
	s_nop 0
	v_add_f32_e32 v50, v50, v51
	s_nop 1
	v_add_f32_dpp v50, v50, v50 quad_perm:[1,0,3,2] row_mask:0xf bank_mask:0xf
	s_nop 1
	v_add_f32_dpp v50, v50, v50 quad_perm:[2,3,0,1] row_mask:0xf bank_mask:0xf
	s_nop 1
	v_add_f32_dpp v50, v50, v50 row_half_mirror row_mask:0xf bank_mask:0xf
	s_nop 1
	v_add_f32_dpp v50, v50, v50 row_mirror row_mask:0xf bank_mask:0xf
	s_nop 1
	v_add_f32_dpp v50, v50, v50 row_bcast:15 row_mask:0xa bank_mask:0xf
	s_nop 1
	v_add_f32_dpp v50, v50, v50 row_bcast:31 row_mask:0xc bank_mask:0xf
	s_nop 1
	v_readlane_b32 vcc_lo, v50, 63
	s_nop 1
	v_mov_b32_e32 v50, vcc_lo
	v_fmamk_f32 v50, v50, 0x3a800000, v66
	v_mul_f32_e32 v51, 0x4f800000, v50
	v_cmp_gt_f32_e32 vcc, s18, v50
	s_nop 1
	v_cndmask_b32_e32 v50, v50, v51, vcc
	v_sqrt_f32_e32 v51, v50
	s_nop 0
	v_add_u32_e32 v72, -1, v51
	v_fma_f32 v73, -v72, v51, v50
	v_cmp_ge_f32_e64 s[0:1], 0, v73
	v_add_u32_e32 v73, 1, v51
	s_nop 0
	v_cndmask_b32_e64 v72, v51, v72, s[0:1]
	v_fma_f32 v51, -v73, v51, v50
	v_cmp_lt_f32_e64 s[0:1], 0, v51
	s_nop 1
	v_cndmask_b32_e64 v51, v72, v73, s[0:1]
	v_mul_f32_e32 v72, 0x37800000, v51
	v_cndmask_b32_e32 v51, v51, v72, vcc
	v_cmp_class_f32_e32 vcc, v50, v67
	s_nop 1
	v_cndmask_b32_e32 v72, v51, v50, vcc
	v_div_scale_f32 v73, s[0:1], v72, v72, 1.0
	v_rcp_f32_e32 v74, v73
	s_lshl_b64 s[0:1], s[10:11], 12
	v_lshl_add_u64 v[50:51], v[52:53], 0, s[0:1]
	v_fma_f32 v75, -v73, v74, 1.0
	v_fmac_f32_e32 v74, v75, v74
	v_div_scale_f32 v75, vcc, 1.0, v72, 1.0
	v_mul_f32_e32 v76, v75, v74
	v_fma_f32 v77, -v73, v76, v75
	v_fmac_f32_e32 v76, v77, v74
	v_fma_f32 v73, -v73, v76, v75
	v_div_fmas_f32 v73, v73, v74, v76
	v_div_fixup_f32 v72, v73, v72, 1.0
	v_pk_mul_f32 v[36:37], v[72:73], v[36:37] op_sel_hi:[0,1]
	v_pk_mul_f32 v[38:39], v[72:73], v[38:39] op_sel_hi:[0,1]
	s_nop 0
	v_pk_fma_f32 v[38:39], v[154:155], v[38:39], v[170:171]
	v_pk_fma_f32 v[36:37], v[152:153], v[36:37], v[168:169]
	global_store_dwordx4 v[50:51], v[36:39], off nt
	s_nop 0
	s_nop 0
	s_nop 0
	v_pk_mul_f32 v[34:35], v[72:73], v[34:35] op_sel_hi:[0,1]
	v_pk_mul_f32 v[32:33], v[72:73], v[32:33] op_sel_hi:[0,1]
	v_pk_mul_f32 v[40:41], v[72:73], v[40:41] op_sel_hi:[0,1]
	s_andn2_b64 vcc, exec, s[8:9]
	s_nop 0
	v_pk_fma_f32 v[32:33], v[156:157], v[32:33], v[172:173]
	v_pk_fma_f32 v[34:35], v[158:159], v[34:35], v[174:175]
	global_store_dwordx4 v[50:51], v[32:35], off offset:1024 nt
	s_nop 0
	s_nop 0
	s_nop 0
	v_pk_mul_f32 v[42:43], v[72:73], v[48:49] op_sel_hi:[0,1]
	v_pk_mul_f32 v[44:45], v[72:73], v[46:47] op_sel_hi:[0,1]
	s_nop 0
	v_pk_fma_f32 v[32:33], v[160:161], v[44:45], v[176:177]
	v_pk_fma_f32 v[34:35], v[162:163], v[42:43], v[178:179]
	global_store_dwordx4 v[50:51], v[32:35], off offset:2048 nt
	s_nop 0
	s_nop 0
	s_nop 0
	v_pk_mul_f32 v[42:43], v[72:73], v[58:59] op_sel_hi:[0,1]
	s_waitcnt vmcnt(7)
	v_pk_fma_f32 v[32:33], v[164:165], v[40:41], v[180:181]
	v_pk_fma_f32 v[34:35], v[166:167], v[42:43], v[182:183]
	global_store_dwordx4 v[50:51], v[32:35], off offset:3072 nt
	s_cbranch_vccnz .LBB0_716
	s_nop 0
	v_mov_b32_e32 v32, v21
	v_mov_b32_e32 v33, v22
	v_mov_b32_e32 v34, v20
	v_mov_b32_e32 v35, v23
	v_pk_add_f32 v[32:33], v[32:33], v[34:35]
	v_mov_b32_e32 v34, v17
	v_mov_b32_e32 v35, v18
	v_mov_b32_e32 v36, v16
	v_mov_b32_e32 v37, v19
	v_pk_add_f32 v[34:35], v[34:35], v[36:37]
	v_add_f32_e32 v32, v32, v33
	v_pk_add_f32 v[34:35], v[34:35], v[34:35] op_sel:[0,1] op_sel_hi:[1,0]
	v_add_f32_e32 v32, 0, v32
	v_add_f32_e32 v36, v28, v29
	v_add_f32_e32 v38, v30, v31
	v_mov_b32_e32 v33, v24
	v_mov_b32_e32 v35, v25
	v_mov_b32_e32 v37, v26
	v_mov_b32_e32 v39, v27
	v_pk_add_f32 v[32:33], v[32:33], v[34:35]
	v_pk_add_f32 v[34:35], v[36:37], v[38:39]
	s_ashr_i32 s7, s6, 31
	v_pk_add_f32 v[32:33], v[32:33], v[34:35]
	s_nop 0
	v_add_f32_e32 v32, v32, v33
	v_mov_b32_e32 v40, v32
	s_nop 1
	v_add_f32_dpp v40, v40, v40 quad_perm:[1,0,3,2] row_mask:0xf bank_mask:0xf
	s_nop 1
	v_add_f32_dpp v40, v40, v40 quad_perm:[2,3,0,1] row_mask:0xf bank_mask:0xf
	s_nop 1
	v_add_f32_dpp v40, v40, v40 row_half_mirror row_mask:0xf bank_mask:0xf
	s_nop 1
	v_add_f32_dpp v40, v40, v40 row_mirror row_mask:0xf bank_mask:0xf
	s_nop 1
	v_add_f32_dpp v40, v40, v40 row_bcast:15 row_mask:0xa bank_mask:0xf
	s_nop 1
	v_add_f32_dpp v40, v40, v40 row_bcast:31 row_mask:0xc bank_mask:0xf
	s_nop 1
	v_readlane_b32 vcc_lo, v40, 63
	s_nop 1
	v_mov_b32_e32 v40, vcc_lo
	v_fmamk_f32 v21, v40, 0xba800000, v21
	v_fmamk_f32 v20, v40, 0xba800000, v20
	v_fmamk_f32 v23, v40, 0xba800000, v23
	v_fmac_f32_e32 v22, 0xba800000, v40
	v_pk_mul_f32 v[32:33], v[22:23], v[22:23]
	v_pk_mul_f32 v[34:35], v[20:21], v[20:21]
	v_fmamk_f32 v17, v40, 0xba800000, v17
	v_fmamk_f32 v16, v40, 0xba800000, v16
	v_fmamk_f32 v19, v40, 0xba800000, v19
	v_pk_mov_b32 v[36:37], v[34:35], v[32:33] op_sel:[1,0]
	v_mov_b32_e32 v35, v33
	v_fmac_f32_e32 v18, 0xba800000, v40
	v_pk_add_f32 v[32:33], v[36:37], v[34:35]
	v_pk_mul_f32 v[34:35], v[18:19], v[18:19]
	v_pk_mul_f32 v[36:37], v[16:17], v[16:17]
	v_fmac_f32_e32 v24, 0xba800000, v40
	v_pk_mov_b32 v[38:39], v[36:37], v[34:35] op_sel:[1,0]
	v_mov_b32_e32 v37, v35
	v_pk_add_f32 v[34:35], v[38:39], v[36:37]
	v_fmamk_f32 v36, v40, 0xba800000, v28
	v_fmamk_f32 v39, v40, 0xba800000, v27
	v_fmamk_f32 v38, v40, 0xba800000, v26
	v_fmamk_f32 v25, v40, 0xba800000, v25
	v_mul_f32_e32 v28, v24, v24
	v_pk_add_f32 v[26:27], v[32:33], v[32:33] op_sel:[0,1] op_sel_hi:[1,0]
	v_fmamk_f32 v37, v40, 0xba800000, v29
	v_fmamk_f32 v31, v40, 0xba800000, v31
	v_fmac_f32_e32 v30, 0xba800000, v40
	v_mul_f32_e32 v40, v25, v25
	v_mov_b32_e32 v27, v28
	v_pk_add_f32 v[28:29], v[34:35], v[34:35] op_sel:[0,1] op_sel_hi:[1,0]
	v_mul_f32_e32 v44, v38, v38
	v_mov_b32_e32 v29, v40
	v_pk_add_f32 v[40:41], v[26:27], v[28:29]
	v_mul_f32_e32 v26, v37, v37
	v_pk_fma_f32 v[42:43], v[36:37], v[36:37], v[26:27] op_sel_hi:[1,1,0]
	v_mul_f32_e32 v26, v31, v31
	v_mov_b32_e32 v43, v44
	v_pk_fma_f32 v[44:45], v[30:31], v[30:31], v[26:27] op_sel_hi:[1,1,0]
	s_nop 0
	s_nop 0
	v_mul_f32_e32 v46, v39, v39
	v_mov_b32_e32 v45, v46
	v_pk_add_f32 v[42:43], v[42:43], v[44:45]
	s_nop 0
	v_pk_add_f32 v[40:41], v[40:41], v[42:43]
	s_nop 0
	v_add_f32_e32 v40, v40, v41
	s_nop 1
	v_add_f32_dpp v40, v40, v40 quad_perm:[1,0,3,2] row_mask:0xf bank_mask:0xf
	s_nop 1
	v_add_f32_dpp v40, v40, v40 quad_perm:[2,3,0,1] row_mask:0xf bank_mask:0xf
	s_nop 1
	v_add_f32_dpp v40, v40, v40 row_half_mirror row_mask:0xf bank_mask:0xf
	s_nop 1
	v_add_f32_dpp v40, v40, v40 row_mirror row_mask:0xf bank_mask:0xf
	s_nop 1
	v_add_f32_dpp v40, v40, v40 row_bcast:15 row_mask:0xa bank_mask:0xf
	s_nop 1
	v_add_f32_dpp v40, v40, v40 row_bcast:31 row_mask:0xc bank_mask:0xf
	s_nop 1
	v_readlane_b32 vcc_lo, v40, 63
	s_nop 1
	v_mov_b32_e32 v40, vcc_lo
	v_fmamk_f32 v40, v40, 0x3a800000, v66
	v_mul_f32_e32 v41, 0x4f800000, v40
	v_cmp_gt_f32_e32 vcc, s18, v40
	s_nop 1
	v_cndmask_b32_e32 v40, v40, v41, vcc
	v_sqrt_f32_e32 v41, v40
	s_nop 0
	v_add_u32_e32 v42, -1, v41
	v_fma_f32 v43, -v42, v41, v40
	v_cmp_ge_f32_e64 s[0:1], 0, v43
	v_add_u32_e32 v43, 1, v41
	s_nop 0
	v_cndmask_b32_e64 v42, v41, v42, s[0:1]
	v_fma_f32 v41, -v43, v41, v40
	v_cmp_lt_f32_e64 s[0:1], 0, v41
	s_nop 1
	v_cndmask_b32_e64 v41, v42, v43, s[0:1]
	v_mul_f32_e32 v42, 0x37800000, v41
	v_cndmask_b32_e32 v41, v41, v42, vcc
	v_cmp_class_f32_e32 vcc, v40, v67
	s_nop 1
	v_cndmask_b32_e32 v42, v41, v40, vcc
	v_div_scale_f32 v43, s[0:1], v42, v42, 1.0
	v_rcp_f32_e32 v44, v43
	s_lshl_b64 s[0:1], s[6:7], 12
	v_lshl_add_u64 v[40:41], v[52:53], 0, s[0:1]
	v_fma_f32 v45, -v43, v44, 1.0
	v_fmac_f32_e32 v44, v45, v44
	v_div_scale_f32 v45, vcc, 1.0, v42, 1.0
	v_mul_f32_e32 v46, v45, v44
	v_fma_f32 v47, -v43, v46, v45
	v_fmac_f32_e32 v46, v47, v44
	v_fma_f32 v43, -v43, v46, v45
	v_div_fmas_f32 v43, v43, v44, v46
	v_div_fixup_f32 v42, v43, v42, 1.0
	v_pk_mul_f32 v[20:21], v[42:43], v[20:21] op_sel_hi:[0,1]
	v_pk_mul_f32 v[22:23], v[42:43], v[22:23] op_sel_hi:[0,1]
	s_nop 0
	v_pk_fma_f32 v[22:23], v[154:155], v[22:23], v[170:171]
	v_pk_fma_f32 v[20:21], v[152:153], v[20:21], v[168:169]
	global_store_dwordx4 v[40:41], v[20:23], off nt
	s_nop 0
	s_nop 0
	s_nop 0
	v_pk_mul_f32 v[18:19], v[42:43], v[18:19] op_sel_hi:[0,1]
	v_pk_mul_f32 v[16:17], v[42:43], v[16:17] op_sel_hi:[0,1]
	v_pk_mul_f32 v[24:25], v[42:43], v[24:25] op_sel_hi:[0,1]
	s_andn2_b64 vcc, exec, s[4:5]
	s_nop 0
	v_pk_fma_f32 v[16:17], v[156:157], v[16:17], v[172:173]
	v_pk_fma_f32 v[18:19], v[158:159], v[18:19], v[174:175]
	global_store_dwordx4 v[40:41], v[16:19], off offset:1024 nt
	s_nop 0
	s_nop 0
	s_nop 0
	v_pk_mul_f32 v[26:27], v[42:43], v[30:31] op_sel_hi:[0,1]
	v_pk_mul_f32 v[28:29], v[42:43], v[36:37] op_sel_hi:[0,1]
	s_nop 0
	v_pk_fma_f32 v[16:17], v[160:161], v[28:29], v[176:177]
	v_pk_fma_f32 v[18:19], v[162:163], v[26:27], v[178:179]
	global_store_dwordx4 v[40:41], v[16:19], off offset:2048 nt
	s_nop 0
	s_nop 0
	s_nop 0
	v_pk_mul_f32 v[26:27], v[42:43], v[38:39] op_sel_hi:[0,1]
	s_waitcnt vmcnt(9)
	v_pk_fma_f32 v[16:17], v[164:165], v[24:25], v[180:181]
	v_pk_fma_f32 v[18:19], v[166:167], v[26:27], v[182:183]
	global_store_dwordx4 v[40:41], v[16:19], off offset:3072 nt
	s_cbranch_vccnz .LBB0_716
	s_nop 0
	v_mov_b32_e32 v16, v9
	v_mov_b32_e32 v17, v10
	v_mov_b32_e32 v18, v8
	v_mov_b32_e32 v19, v11
	v_pk_add_f32 v[16:17], v[16:17], v[18:19]
	v_mov_b32_e32 v18, v1
	v_mov_b32_e32 v19, v2
	v_mov_b32_e32 v20, v0
	v_mov_b32_e32 v21, v3
	v_pk_add_f32 v[18:19], v[18:19], v[20:21]
	v_add_f32_e32 v16, v16, v17
	v_pk_add_f32 v[18:19], v[18:19], v[18:19] op_sel:[0,1] op_sel_hi:[1,0]
	v_add_f32_e32 v16, 0, v16
	v_add_f32_e32 v20, v12, v13
	v_add_f32_e32 v22, v14, v15
	v_mov_b32_e32 v17, v4
	v_mov_b32_e32 v19, v5
	v_mov_b32_e32 v21, v6
	v_mov_b32_e32 v23, v7
	v_pk_add_f32 v[16:17], v[16:17], v[18:19]
	v_pk_add_f32 v[18:19], v[20:21], v[22:23]
	s_ashr_i32 s3, s2, 31
	v_pk_add_f32 v[16:17], v[16:17], v[18:19]
	s_nop 0
	v_add_f32_e32 v16, v16, v17
	v_mov_b32_e32 v26, v16
	s_nop 1
	v_add_f32_dpp v26, v26, v26 quad_perm:[1,0,3,2] row_mask:0xf bank_mask:0xf
	s_nop 1
	v_add_f32_dpp v26, v26, v26 quad_perm:[2,3,0,1] row_mask:0xf bank_mask:0xf
	s_nop 1
	v_add_f32_dpp v26, v26, v26 row_half_mirror row_mask:0xf bank_mask:0xf
	s_nop 1
	v_add_f32_dpp v26, v26, v26 row_mirror row_mask:0xf bank_mask:0xf
	s_nop 1
	v_add_f32_dpp v26, v26, v26 row_bcast:15 row_mask:0xa bank_mask:0xf
	s_nop 1
	v_add_f32_dpp v26, v26, v26 row_bcast:31 row_mask:0xc bank_mask:0xf
	s_nop 1
	v_readlane_b32 vcc_lo, v26, 63
	s_nop 1
	v_mov_b32_e32 v26, vcc_lo
	v_fmamk_f32 v21, v26, 0xba800000, v9
	v_fmamk_f32 v20, v26, 0xba800000, v8
	v_fmamk_f32 v11, v26, 0xba800000, v11
	v_fmac_f32_e32 v10, 0xba800000, v26
	v_pk_mul_f32 v[8:9], v[10:11], v[10:11]
	v_pk_mul_f32 v[16:17], v[20:21], v[20:21]
	v_fmamk_f32 v1, v26, 0xba800000, v1
	v_fmamk_f32 v0, v26, 0xba800000, v0
	v_fmamk_f32 v3, v26, 0xba800000, v3
	v_pk_mov_b32 v[18:19], v[16:17], v[8:9] op_sel:[1,0]
	v_mov_b32_e32 v17, v9
	v_fmac_f32_e32 v2, 0xba800000, v26
	v_pk_add_f32 v[8:9], v[18:19], v[16:17]
	v_pk_mul_f32 v[16:17], v[2:3], v[2:3]
	v_pk_mul_f32 v[18:19], v[0:1], v[0:1]
	v_fmamk_f32 v5, v26, 0xba800000, v5
	v_pk_mov_b32 v[22:23], v[18:19], v[16:17] op_sel:[1,0]
	v_mov_b32_e32 v19, v17
	v_pk_add_f32 v[16:17], v[22:23], v[18:19]
	v_fmac_f32_e32 v4, 0xba800000, v26
	v_fmamk_f32 v23, v26, 0xba800000, v13
	v_fmamk_f32 v22, v26, 0xba800000, v12
	v_fmamk_f32 v25, v26, 0xba800000, v7
	v_fmamk_f32 v24, v26, 0xba800000, v6
	v_mul_f32_e32 v12, v4, v4
	v_mul_f32_e32 v13, v5, v5
	v_pk_add_f32 v[6:7], v[8:9], v[8:9] op_sel:[0,1] op_sel_hi:[1,0]
	v_pk_add_f32 v[8:9], v[16:17], v[16:17] op_sel:[0,1] op_sel_hi:[1,0]
	v_mov_b32_e32 v7, v12
	v_mov_b32_e32 v9, v13
	v_fmamk_f32 v15, v26, 0xba800000, v15
	v_pk_add_f32 v[12:13], v[6:7], v[8:9]
	v_mul_f32_e32 v6, v23, v23
	v_fmac_f32_e32 v14, 0xba800000, v26
	v_mul_f32_e32 v18, v24, v24
	v_pk_fma_f32 v[26:27], v[22:23], v[22:23], v[6:7] op_sel_hi:[1,1,0]
	v_mul_f32_e32 v6, v15, v15
	v_mov_b32_e32 v27, v18
	v_pk_fma_f32 v[28:29], v[14:15], v[14:15], v[6:7] op_sel_hi:[1,1,0]
	s_nop 0
	s_nop 0
	v_mul_f32_e32 v30, v25, v25
	v_mov_b32_e32 v29, v30
	v_pk_add_f32 v[26:27], v[26:27], v[28:29]
	s_nop 0
	v_pk_add_f32 v[12:13], v[12:13], v[26:27]
	s_nop 0
	v_add_f32_e32 v12, v12, v13
	s_nop 1
	v_add_f32_dpp v12, v12, v12 quad_perm:[1,0,3,2] row_mask:0xf bank_mask:0xf
	s_nop 1
	v_add_f32_dpp v12, v12, v12 quad_perm:[2,3,0,1] row_mask:0xf bank_mask:0xf
	s_nop 1
	v_add_f32_dpp v12, v12, v12 row_half_mirror row_mask:0xf bank_mask:0xf
	s_nop 1
	v_add_f32_dpp v12, v12, v12 row_mirror row_mask:0xf bank_mask:0xf
	s_nop 1
	v_add_f32_dpp v12, v12, v12 row_bcast:15 row_mask:0xa bank_mask:0xf
	s_nop 1
	v_add_f32_dpp v12, v12, v12 row_bcast:31 row_mask:0xc bank_mask:0xf
	s_nop 1
	v_readlane_b32 vcc_lo, v12, 63
	s_nop 1
	v_mov_b32_e32 v12, vcc_lo
	v_fmamk_f32 v12, v12, 0x3a800000, v66
	v_mul_f32_e32 v13, 0x4f800000, v12
	v_cmp_gt_f32_e32 vcc, s18, v12
	s_nop 1
	v_cndmask_b32_e32 v12, v12, v13, vcc
	v_sqrt_f32_e32 v13, v12
	s_nop 0
	v_add_u32_e32 v26, -1, v13
	v_fma_f32 v27, -v26, v13, v12
	v_cmp_ge_f32_e64 s[0:1], 0, v27
	v_add_u32_e32 v27, 1, v13
	s_nop 0
	v_cndmask_b32_e64 v26, v13, v26, s[0:1]
	v_fma_f32 v13, -v27, v13, v12
	v_cmp_lt_f32_e64 s[0:1], 0, v13
	s_nop 1
	v_cndmask_b32_e64 v13, v26, v27, s[0:1]
	v_mul_f32_e32 v26, 0x37800000, v13
	v_cndmask_b32_e32 v13, v13, v26, vcc
	v_cmp_class_f32_e32 vcc, v12, v67
	s_nop 1
	v_cndmask_b32_e32 v12, v13, v12, vcc
	v_div_scale_f32 v13, s[0:1], v12, v12, 1.0
	v_rcp_f32_e32 v28, v13
	s_lshl_b64 s[0:1], s[2:3], 12
	v_lshl_add_u64 v[26:27], v[52:53], 0, s[0:1]
	v_fma_f32 v29, -v13, v28, 1.0
	v_fmac_f32_e32 v28, v29, v28
	v_div_scale_f32 v29, vcc, 1.0, v12, 1.0
	v_mul_f32_e32 v30, v29, v28
	v_fma_f32 v31, -v13, v30, v29
	v_fmac_f32_e32 v30, v31, v28
	v_fma_f32 v13, -v13, v30, v29
	v_div_fmas_f32 v13, v13, v28, v30
	v_div_fixup_f32 v28, v13, v12, 1.0
	v_pk_mul_f32 v[12:13], v[28:29], v[20:21] op_sel_hi:[0,1]
	v_pk_mul_f32 v[10:11], v[28:29], v[10:11] op_sel_hi:[0,1]
	s_nop 0
	v_pk_fma_f32 v[8:9], v[154:155], v[10:11], v[170:171]
	v_pk_fma_f32 v[6:7], v[152:153], v[12:13], v[168:169]
	global_store_dwordx4 v[26:27], v[6:9], off nt
	s_nop 0
	s_nop 0
	s_nop 0
	v_pk_mul_f32 v[2:3], v[28:29], v[2:3] op_sel_hi:[0,1]
	v_pk_mul_f32 v[0:1], v[28:29], v[0:1] op_sel_hi:[0,1]
	v_pk_mul_f32 v[4:5], v[28:29], v[4:5] op_sel_hi:[0,1]
	s_nop 0
	v_pk_fma_f32 v[0:1], v[156:157], v[0:1], v[172:173]
	v_pk_fma_f32 v[2:3], v[158:159], v[2:3], v[174:175]
	global_store_dwordx4 v[26:27], v[0:3], off offset:1024 nt
	s_nop 0
	s_nop 0
	s_nop 0
	v_pk_mul_f32 v[10:11], v[28:29], v[14:15] op_sel_hi:[0,1]
	v_pk_mul_f32 v[12:13], v[28:29], v[22:23] op_sel_hi:[0,1]
	s_nop 0
	v_pk_fma_f32 v[0:1], v[160:161], v[12:13], v[176:177]
	v_pk_fma_f32 v[2:3], v[162:163], v[10:11], v[178:179]
	global_store_dwordx4 v[26:27], v[0:3], off offset:2048 nt
	s_nop 0
	s_nop 0
	s_nop 0
	v_pk_mul_f32 v[10:11], v[28:29], v[24:25] op_sel_hi:[0,1]
	s_nop 0
	v_pk_fma_f32 v[0:1], v[164:165], v[4:5], v[180:181]
	v_pk_fma_f32 v[2:3], v[166:167], v[10:11], v[182:183]
	global_store_dwordx4 v[26:27], v[0:3], off offset:3072 nt
	s_branch .LBB0_716
